# mix stage-2 Fourier epilogue: row-major 16B gate loads/stores via wave-private LDS tile (2-byte accesses only in LDS)
# baseline (speedup 1.0000x reference)
.LBB0_1152:
	s_and_b64 vcc, exec, s[4:5]
	s_cbranch_vccz .LBB0_1154
	v_lshrrev_b32_e32 v146, 6, v144
	s_movk_i32 s5, 0x110
	s_nop 0
	v_readfirstlane_b32 s4, v146
	s_mul_i32 s4, s4, 0x2200
	s_add_i32 s4, s4, 32
	v_and_b32_e32 v147, 63, v144
	v_lshrrev_b32_e32 v148, 4, v147
	v_and_b32_e32 v149, 15, v147
	v_lshlrev_b32_e32 v149, 4, v149
	v_mad_u32_u24 v0, v148, s5, v149
	v_add_u32_e32 v0, s4, v0
	v_and_b32_e32 v150, 31, v147
	v_lshrrev_b32_e32 v151, 5, v147
	v_lshlrev_b32_e32 v150, 1, v150
	v_mul_u32_u24_e32 v151, 0x440, v151
	v_add3_u32 v1, v150, v151, s4
	v_bfe_u32 v152, v146, 0, 2
	v_lshrrev_b32_e32 v153, 2, v146
	v_lshl_add_u32 v149, v153, 8, v149
	v_mad_u32_u24 v2, v152, s92, v149
	v_lshl_add_u32 v3, v152, 11, v149
	s_mov_b32 s5, 0x28000
	v_mad_u32_u24 v2, v148, s5, v2
	v_lshl_add_u32 v3, v148, 17, v3
	v_readlane_b32 s70, v254, 8
	v_readlane_b32 s71, v254, 9
	s_mul_i32 s4, s68, 0xa00
	s_add_u32 s70, s70, s4
	s_addc_u32 s71, s71, 0
	s_lshl_b32 s4, s68, 11
	s_add_u32 s72, s46, s4
	s_addc_u32 s73, s47, 0
	v_mov_b32_e32 v210, 0
	v_mov_b32_e32 v211, 0
	v_mov_b32_e32 v212, 0
	v_mov_b32_e32 v213, 0
	v_mov_b32_e32 v214, 0
	v_mov_b32_e32 v215, 0
	v_mov_b32_e32 v216, 0
	v_mov_b32_e32 v217, 0
	v_mov_b32_e32 v218, 0
	v_mov_b32_e32 v219, 0
	v_mov_b32_e32 v220, 0
	v_mov_b32_e32 v221, 0
	v_mov_b32_e32 v222, 0
	v_mov_b32_e32 v223, 0
	v_mov_b32_e32 v224, 0
	v_mov_b32_e32 v225, 0
	s_add_u32 s74, s70, 0x0
	s_addc_u32 s75, s71, 0
	global_load_dwordx4 v[146:149], v2, s[74:75]
	s_add_u32 s74, s70, 0xa0000
	s_addc_u32 s75, s71, 0
	global_load_dwordx4 v[150:153], v2, s[74:75]
	s_add_u32 s74, s70, 0x140000
	s_addc_u32 s75, s71, 0
	global_load_dwordx4 v[154:157], v2, s[74:75]
	s_add_u32 s74, s70, 0x1e0000
	s_addc_u32 s75, s71, 0
	global_load_dwordx4 v[158:161], v2, s[74:75]
	s_add_u32 s74, s70, 0x280000
	s_addc_u32 s75, s71, 0
	global_load_dwordx4 v[162:165], v2, s[74:75]
	s_add_u32 s74, s70, 0x320000
	s_addc_u32 s75, s71, 0
	global_load_dwordx4 v[166:169], v2, s[74:75]
	s_add_u32 s74, s70, 0x3c0000
	s_addc_u32 s75, s71, 0
	global_load_dwordx4 v[170:173], v2, s[74:75]
	s_add_u32 s74, s70, 0x460000
	s_addc_u32 s75, s71, 0
	global_load_dwordx4 v[174:177], v2, s[74:75]
	s_add_u32 s74, s70, 0x500000
	s_addc_u32 s75, s71, 0
	global_load_dwordx4 v[178:181], v2, s[74:75]
	s_add_u32 s74, s70, 0x5a0000
	s_addc_u32 s75, s71, 0
	global_load_dwordx4 v[182:185], v2, s[74:75]
	s_add_u32 s74, s70, 0x640000
	s_addc_u32 s75, s71, 0
	global_load_dwordx4 v[186:189], v2, s[74:75]
	s_add_u32 s74, s70, 0x6e0000
	s_addc_u32 s75, s71, 0
	global_load_dwordx4 v[190:193], v2, s[74:75]
	s_add_u32 s74, s70, 0x780000
	s_addc_u32 s75, s71, 0
	global_load_dwordx4 v[194:197], v2, s[74:75]
	s_add_u32 s74, s70, 0x820000
	s_addc_u32 s75, s71, 0
	global_load_dwordx4 v[198:201], v2, s[74:75]
	s_add_u32 s74, s70, 0x8c0000
	s_addc_u32 s75, s71, 0
	global_load_dwordx4 v[202:205], v2, s[74:75]
	s_add_u32 s74, s70, 0x960000
	s_addc_u32 s75, s71, 0
	global_load_dwordx4 v[206:209], v2, s[74:75]
	s_waitcnt vmcnt(15)
	ds_write_b128 v0, v[146:149]
	s_waitcnt vmcnt(14)
	ds_write_b128 v0, v[150:153] offset:1088
	s_waitcnt vmcnt(13)
	ds_write_b128 v0, v[154:157] offset:2176
	s_waitcnt vmcnt(12)
	ds_write_b128 v0, v[158:161] offset:3264
	s_waitcnt vmcnt(11)
	ds_write_b128 v0, v[162:165] offset:4352
	s_waitcnt vmcnt(10)
	ds_write_b128 v0, v[166:169] offset:5440
	s_waitcnt vmcnt(9)
	ds_write_b128 v0, v[170:173] offset:6528
	s_waitcnt vmcnt(8)
	ds_write_b128 v0, v[174:177] offset:7616
	s_waitcnt lgkmcnt(7)
	ds_read_u16_d16_hi v210, v1
	ds_read_u16_d16_hi v211, v1 offset:272
	ds_read_u16_d16_hi v212, v1 offset:544
	ds_read_u16_d16_hi v213, v1 offset:816
	ds_read_u16_d16_hi v214, v1 offset:2176
	ds_read_u16_d16_hi v215, v1 offset:2448
	ds_read_u16_d16_hi v216, v1 offset:2720
	ds_read_u16_d16_hi v217, v1 offset:2992
	s_waitcnt lgkmcnt(7)
	v_mul_f32_e32 v226, v118, v210
	v_cvt_pk_bf16_f32 v226, v226, v226
	ds_write_b16 v1, v226
	s_waitcnt lgkmcnt(7)
	v_mul_f32_e32 v227, v119, v211
	v_cvt_pk_bf16_f32 v227, v227, v227
	ds_write_b16 v1, v227 offset:272
	s_waitcnt lgkmcnt(7)
	v_mul_f32_e32 v228, v120, v212
	v_cvt_pk_bf16_f32 v228, v228, v228
	ds_write_b16 v1, v228 offset:544
	s_waitcnt lgkmcnt(7)
	v_mul_f32_e32 v229, v121, v213
	v_cvt_pk_bf16_f32 v229, v229, v229
	ds_write_b16 v1, v229 offset:816
	s_waitcnt lgkmcnt(7)
	v_mul_f32_e32 v226, v122, v214
	v_cvt_pk_bf16_f32 v226, v226, v226
	ds_write_b16 v1, v226 offset:2176
	s_waitcnt lgkmcnt(7)
	v_mul_f32_e32 v227, v123, v215
	v_cvt_pk_bf16_f32 v227, v227, v227
	ds_write_b16 v1, v227 offset:2448
	s_waitcnt lgkmcnt(7)
	v_mul_f32_e32 v228, v124, v216
	v_cvt_pk_bf16_f32 v228, v228, v228
	ds_write_b16 v1, v228 offset:2720
	s_waitcnt lgkmcnt(7)
	v_mul_f32_e32 v229, v125, v217
	v_cvt_pk_bf16_f32 v229, v229, v229
	ds_write_b16 v1, v229 offset:2992
	s_waitcnt lgkmcnt(7)
	ds_read_u16_d16_hi v218, v1 offset:4352
	ds_read_u16_d16_hi v219, v1 offset:4624
	ds_read_u16_d16_hi v220, v1 offset:4896
	ds_read_u16_d16_hi v221, v1 offset:5168
	ds_read_u16_d16_hi v222, v1 offset:6528
	ds_read_u16_d16_hi v223, v1 offset:6800
	ds_read_u16_d16_hi v224, v1 offset:7072
	ds_read_u16_d16_hi v225, v1 offset:7344
	s_waitcnt lgkmcnt(7)
	v_mul_f32_e32 v226, v126, v218
	v_cvt_pk_bf16_f32 v226, v226, v226
	ds_write_b16 v1, v226 offset:4352
	s_waitcnt lgkmcnt(7)
	v_mul_f32_e32 v227, v127, v219
	v_cvt_pk_bf16_f32 v227, v227, v227
	ds_write_b16 v1, v227 offset:4624
	s_waitcnt lgkmcnt(7)
	v_mul_f32_e32 v228, v128, v220
	v_cvt_pk_bf16_f32 v228, v228, v228
	ds_write_b16 v1, v228 offset:4896
	s_waitcnt lgkmcnt(7)
	v_mul_f32_e32 v229, v129, v221
	v_cvt_pk_bf16_f32 v229, v229, v229
	ds_write_b16 v1, v229 offset:5168
	s_waitcnt lgkmcnt(7)
	v_mul_f32_e32 v226, v130, v222
	v_cvt_pk_bf16_f32 v226, v226, v226
	ds_write_b16 v1, v226 offset:6528
	s_waitcnt lgkmcnt(7)
	v_mul_f32_e32 v227, v131, v223
	v_cvt_pk_bf16_f32 v227, v227, v227
	ds_write_b16 v1, v227 offset:6800
	s_waitcnt lgkmcnt(7)
	v_mul_f32_e32 v228, v132, v224
	v_cvt_pk_bf16_f32 v228, v228, v228
	ds_write_b16 v1, v228 offset:7072
	s_waitcnt lgkmcnt(7)
	v_mul_f32_e32 v229, v133, v225
	v_cvt_pk_bf16_f32 v229, v229, v229
	ds_write_b16 v1, v229 offset:7344
	s_waitcnt lgkmcnt(7)
	ds_read_u16_d16_hi v210, v1 offset:64
	ds_read_u16_d16_hi v211, v1 offset:336
	ds_read_u16_d16_hi v212, v1 offset:608
	ds_read_u16_d16_hi v213, v1 offset:880
	ds_read_u16_d16_hi v214, v1 offset:2240
	ds_read_u16_d16_hi v215, v1 offset:2512
	ds_read_u16_d16_hi v216, v1 offset:2784
	ds_read_u16_d16_hi v217, v1 offset:3056
	s_waitcnt lgkmcnt(7)
	v_mul_f32_e32 v226, v86, v210
	v_cvt_pk_bf16_f32 v226, v226, v226
	ds_write_b16 v1, v226 offset:64
	s_waitcnt lgkmcnt(7)
	v_mul_f32_e32 v227, v87, v211
	v_cvt_pk_bf16_f32 v227, v227, v227
	ds_write_b16 v1, v227 offset:336
	s_waitcnt lgkmcnt(7)
	v_mul_f32_e32 v228, v88, v212
	v_cvt_pk_bf16_f32 v228, v228, v228
	ds_write_b16 v1, v228 offset:608
	s_waitcnt lgkmcnt(7)
	v_mul_f32_e32 v229, v89, v213
	v_cvt_pk_bf16_f32 v229, v229, v229
	ds_write_b16 v1, v229 offset:880
	s_waitcnt lgkmcnt(7)
	v_mul_f32_e32 v226, v90, v214
	v_cvt_pk_bf16_f32 v226, v226, v226
	ds_write_b16 v1, v226 offset:2240
	s_waitcnt lgkmcnt(7)
	v_mul_f32_e32 v227, v91, v215
	v_cvt_pk_bf16_f32 v227, v227, v227
	ds_write_b16 v1, v227 offset:2512
	s_waitcnt lgkmcnt(7)
	v_mul_f32_e32 v228, v92, v216
	v_cvt_pk_bf16_f32 v228, v228, v228
	ds_write_b16 v1, v228 offset:2784
	s_waitcnt lgkmcnt(7)
	v_mul_f32_e32 v229, v93, v217
	v_cvt_pk_bf16_f32 v229, v229, v229
	ds_write_b16 v1, v229 offset:3056
	s_waitcnt lgkmcnt(7)
	ds_read_u16_d16_hi v218, v1 offset:4416
	ds_read_u16_d16_hi v219, v1 offset:4688
	ds_read_u16_d16_hi v220, v1 offset:4960
	ds_read_u16_d16_hi v221, v1 offset:5232
	ds_read_u16_d16_hi v222, v1 offset:6592
	ds_read_u16_d16_hi v223, v1 offset:6864
	ds_read_u16_d16_hi v224, v1 offset:7136
	ds_read_u16_d16_hi v225, v1 offset:7408
	s_waitcnt lgkmcnt(7)
	v_mul_f32_e32 v226, v94, v218
	v_cvt_pk_bf16_f32 v226, v226, v226
	ds_write_b16 v1, v226 offset:4416
	s_waitcnt lgkmcnt(7)
	v_mul_f32_e32 v227, v95, v219
	v_cvt_pk_bf16_f32 v227, v227, v227
	ds_write_b16 v1, v227 offset:4688
	s_waitcnt lgkmcnt(7)
	v_mul_f32_e32 v228, v96, v220
	v_cvt_pk_bf16_f32 v228, v228, v228
	ds_write_b16 v1, v228 offset:4960
	s_waitcnt lgkmcnt(7)
	v_mul_f32_e32 v229, v97, v221
	v_cvt_pk_bf16_f32 v229, v229, v229
	ds_write_b16 v1, v229 offset:5232
	s_waitcnt lgkmcnt(7)
	v_mul_f32_e32 v226, v98, v222
	v_cvt_pk_bf16_f32 v226, v226, v226
	ds_write_b16 v1, v226 offset:6592
	s_waitcnt lgkmcnt(7)
	v_mul_f32_e32 v227, v99, v223
	v_cvt_pk_bf16_f32 v227, v227, v227
	ds_write_b16 v1, v227 offset:6864
	s_waitcnt lgkmcnt(7)
	v_mul_f32_e32 v228, v100, v224
	v_cvt_pk_bf16_f32 v228, v228, v228
	ds_write_b16 v1, v228 offset:7136
	s_waitcnt lgkmcnt(7)
	v_mul_f32_e32 v229, v101, v225
	v_cvt_pk_bf16_f32 v229, v229, v229
	ds_write_b16 v1, v229 offset:7408
	s_waitcnt lgkmcnt(7)
	ds_read_u16_d16_hi v210, v1 offset:128
	ds_read_u16_d16_hi v211, v1 offset:400
	ds_read_u16_d16_hi v212, v1 offset:672
	ds_read_u16_d16_hi v213, v1 offset:944
	ds_read_u16_d16_hi v214, v1 offset:2304
	ds_read_u16_d16_hi v215, v1 offset:2576
	ds_read_u16_d16_hi v216, v1 offset:2848
	ds_read_u16_d16_hi v217, v1 offset:3120
	s_waitcnt lgkmcnt(7)
	v_mul_f32_e32 v226, v54, v210
	v_cvt_pk_bf16_f32 v226, v226, v226
	ds_write_b16 v1, v226 offset:128
	s_waitcnt lgkmcnt(7)
	v_mul_f32_e32 v227, v55, v211
	v_cvt_pk_bf16_f32 v227, v227, v227
	ds_write_b16 v1, v227 offset:400
	s_waitcnt lgkmcnt(7)
	v_mul_f32_e32 v228, v56, v212
	v_cvt_pk_bf16_f32 v228, v228, v228
	ds_write_b16 v1, v228 offset:672
	s_waitcnt lgkmcnt(7)
	v_mul_f32_e32 v229, v57, v213
	v_cvt_pk_bf16_f32 v229, v229, v229
	ds_write_b16 v1, v229 offset:944
	s_waitcnt lgkmcnt(7)
	v_mul_f32_e32 v226, v58, v214
	v_cvt_pk_bf16_f32 v226, v226, v226
	ds_write_b16 v1, v226 offset:2304
	s_waitcnt lgkmcnt(7)
	v_mul_f32_e32 v227, v59, v215
	v_cvt_pk_bf16_f32 v227, v227, v227
	ds_write_b16 v1, v227 offset:2576
	s_waitcnt lgkmcnt(7)
	v_mul_f32_e32 v228, v60, v216
	v_cvt_pk_bf16_f32 v228, v228, v228
	ds_write_b16 v1, v228 offset:2848
	s_waitcnt lgkmcnt(7)
	v_mul_f32_e32 v229, v61, v217
	v_cvt_pk_bf16_f32 v229, v229, v229
	ds_write_b16 v1, v229 offset:3120
	s_waitcnt lgkmcnt(7)
	ds_read_u16_d16_hi v218, v1 offset:4480
	ds_read_u16_d16_hi v219, v1 offset:4752
	ds_read_u16_d16_hi v220, v1 offset:5024
	ds_read_u16_d16_hi v221, v1 offset:5296
	ds_read_u16_d16_hi v222, v1 offset:6656
	ds_read_u16_d16_hi v223, v1 offset:6928
	ds_read_u16_d16_hi v224, v1 offset:7200
	ds_read_u16_d16_hi v225, v1 offset:7472
	s_waitcnt lgkmcnt(7)
	v_mul_f32_e32 v226, v62, v218
	v_cvt_pk_bf16_f32 v226, v226, v226
	ds_write_b16 v1, v226 offset:4480
	s_waitcnt lgkmcnt(7)
	v_mul_f32_e32 v227, v63, v219
	v_cvt_pk_bf16_f32 v227, v227, v227
	ds_write_b16 v1, v227 offset:4752
	s_waitcnt lgkmcnt(7)
	v_mul_f32_e32 v228, v64, v220
	v_cvt_pk_bf16_f32 v228, v228, v228
	ds_write_b16 v1, v228 offset:5024
	s_waitcnt lgkmcnt(7)
	v_mul_f32_e32 v229, v65, v221
	v_cvt_pk_bf16_f32 v229, v229, v229
	ds_write_b16 v1, v229 offset:5296
	s_waitcnt lgkmcnt(7)
	v_mul_f32_e32 v226, v66, v222
	v_cvt_pk_bf16_f32 v226, v226, v226
	ds_write_b16 v1, v226 offset:6656
	s_waitcnt lgkmcnt(7)
	v_mul_f32_e32 v227, v67, v223
	v_cvt_pk_bf16_f32 v227, v227, v227
	ds_write_b16 v1, v227 offset:6928
	s_waitcnt lgkmcnt(7)
	v_mul_f32_e32 v228, v68, v224
	v_cvt_pk_bf16_f32 v228, v228, v228
	ds_write_b16 v1, v228 offset:7200
	s_waitcnt lgkmcnt(7)
	v_mul_f32_e32 v229, v69, v225
	v_cvt_pk_bf16_f32 v229, v229, v229
	ds_write_b16 v1, v229 offset:7472
	s_waitcnt lgkmcnt(7)
	ds_read_u16_d16_hi v210, v1 offset:192
	ds_read_u16_d16_hi v211, v1 offset:464
	ds_read_u16_d16_hi v212, v1 offset:736
	ds_read_u16_d16_hi v213, v1 offset:1008
	ds_read_u16_d16_hi v214, v1 offset:2368
	ds_read_u16_d16_hi v215, v1 offset:2640
	ds_read_u16_d16_hi v216, v1 offset:2912
	ds_read_u16_d16_hi v217, v1 offset:3184
	s_waitcnt lgkmcnt(7)
	v_mul_f32_e32 v226, v22, v210
	v_cvt_pk_bf16_f32 v226, v226, v226
	ds_write_b16 v1, v226 offset:192
	s_waitcnt lgkmcnt(7)
	v_mul_f32_e32 v227, v23, v211
	v_cvt_pk_bf16_f32 v227, v227, v227
	ds_write_b16 v1, v227 offset:464
	s_waitcnt lgkmcnt(7)
	v_mul_f32_e32 v228, v24, v212
	v_cvt_pk_bf16_f32 v228, v228, v228
	ds_write_b16 v1, v228 offset:736
	s_waitcnt lgkmcnt(7)
	v_mul_f32_e32 v229, v25, v213
	v_cvt_pk_bf16_f32 v229, v229, v229
	ds_write_b16 v1, v229 offset:1008
	s_waitcnt lgkmcnt(7)
	v_mul_f32_e32 v226, v26, v214
	v_cvt_pk_bf16_f32 v226, v226, v226
	ds_write_b16 v1, v226 offset:2368
	s_waitcnt lgkmcnt(7)
	v_mul_f32_e32 v227, v27, v215
	v_cvt_pk_bf16_f32 v227, v227, v227
	ds_write_b16 v1, v227 offset:2640
	s_waitcnt lgkmcnt(7)
	v_mul_f32_e32 v228, v28, v216
	v_cvt_pk_bf16_f32 v228, v228, v228
	ds_write_b16 v1, v228 offset:2912
	s_waitcnt lgkmcnt(7)
	v_mul_f32_e32 v229, v29, v217
	v_cvt_pk_bf16_f32 v229, v229, v229
	ds_write_b16 v1, v229 offset:3184
	s_waitcnt lgkmcnt(7)
	ds_read_u16_d16_hi v218, v1 offset:4544
	ds_read_u16_d16_hi v219, v1 offset:4816
	ds_read_u16_d16_hi v220, v1 offset:5088
	ds_read_u16_d16_hi v221, v1 offset:5360
	ds_read_u16_d16_hi v222, v1 offset:6720
	ds_read_u16_d16_hi v223, v1 offset:6992
	ds_read_u16_d16_hi v224, v1 offset:7264
	ds_read_u16_d16_hi v225, v1 offset:7536
	s_waitcnt lgkmcnt(7)
	v_mul_f32_e32 v226, v30, v218
	v_cvt_pk_bf16_f32 v226, v226, v226
	ds_write_b16 v1, v226 offset:4544
	s_waitcnt lgkmcnt(7)
	v_mul_f32_e32 v227, v31, v219
	v_cvt_pk_bf16_f32 v227, v227, v227
	ds_write_b16 v1, v227 offset:4816
	s_waitcnt lgkmcnt(7)
	v_mul_f32_e32 v228, v32, v220
	v_cvt_pk_bf16_f32 v228, v228, v228
	ds_write_b16 v1, v228 offset:5088
	s_waitcnt lgkmcnt(7)
	v_mul_f32_e32 v229, v33, v221
	v_cvt_pk_bf16_f32 v229, v229, v229
	ds_write_b16 v1, v229 offset:5360
	s_waitcnt lgkmcnt(7)
	v_mul_f32_e32 v226, v34, v222
	v_cvt_pk_bf16_f32 v226, v226, v226
	ds_write_b16 v1, v226 offset:6720
	s_waitcnt lgkmcnt(7)
	v_mul_f32_e32 v227, v35, v223
	v_cvt_pk_bf16_f32 v227, v227, v227
	ds_write_b16 v1, v227 offset:6992
	s_waitcnt lgkmcnt(7)
	v_mul_f32_e32 v228, v36, v224
	v_cvt_pk_bf16_f32 v228, v228, v228
	ds_write_b16 v1, v228 offset:7264
	s_waitcnt lgkmcnt(7)
	v_mul_f32_e32 v229, v37, v225
	v_cvt_pk_bf16_f32 v229, v229, v229
	ds_write_b16 v1, v229 offset:7536
	s_waitcnt lgkmcnt(7)
	ds_read_b128 v[146:149], v0
	ds_read_b128 v[150:153], v0 offset:1088
	ds_read_b128 v[154:157], v0 offset:2176
	ds_read_b128 v[158:161], v0 offset:3264
	ds_read_b128 v[162:165], v0 offset:4352
	ds_read_b128 v[166:169], v0 offset:5440
	ds_read_b128 v[170:173], v0 offset:6528
	ds_read_b128 v[174:177], v0 offset:7616
	s_add_u32 s74, s72, 0x0
	s_addc_u32 s75, s73, 0
	s_waitcnt lgkmcnt(7)
	global_store_dwordx4 v3, v[146:149], s[74:75]
	s_add_u32 s74, s72, 0x80000
	s_addc_u32 s75, s73, 0
	s_waitcnt lgkmcnt(6)
	global_store_dwordx4 v3, v[150:153], s[74:75]
	s_add_u32 s74, s72, 0x100000
	s_addc_u32 s75, s73, 0
	s_waitcnt lgkmcnt(5)
	global_store_dwordx4 v3, v[154:157], s[74:75]
	s_add_u32 s74, s72, 0x180000
	s_addc_u32 s75, s73, 0
	s_waitcnt lgkmcnt(4)
	global_store_dwordx4 v3, v[158:161], s[74:75]
	s_add_u32 s74, s72, 0x200000
	s_addc_u32 s75, s73, 0
	s_waitcnt lgkmcnt(3)
	global_store_dwordx4 v3, v[162:165], s[74:75]
	s_add_u32 s74, s72, 0x280000
	s_addc_u32 s75, s73, 0
	s_waitcnt lgkmcnt(2)
	global_store_dwordx4 v3, v[166:169], s[74:75]
	s_add_u32 s74, s72, 0x300000
	s_addc_u32 s75, s73, 0
	s_waitcnt lgkmcnt(1)
	global_store_dwordx4 v3, v[170:173], s[74:75]
	s_add_u32 s74, s72, 0x380000
	s_addc_u32 s75, s73, 0
	s_waitcnt lgkmcnt(0)
	global_store_dwordx4 v3, v[174:177], s[74:75]
	s_waitcnt vmcnt(15)
	ds_write_b128 v0, v[178:181]
	s_waitcnt vmcnt(14)
	ds_write_b128 v0, v[182:185] offset:1088
	s_waitcnt vmcnt(13)
	ds_write_b128 v0, v[186:189] offset:2176
	s_waitcnt vmcnt(12)
	ds_write_b128 v0, v[190:193] offset:3264
	s_waitcnt vmcnt(11)
	ds_write_b128 v0, v[194:197] offset:4352
	s_waitcnt vmcnt(10)
	ds_write_b128 v0, v[198:201] offset:5440
	s_waitcnt vmcnt(9)
	ds_write_b128 v0, v[202:205] offset:6528
	s_waitcnt vmcnt(8)
	ds_write_b128 v0, v[206:209] offset:7616
	s_waitcnt lgkmcnt(7)
	ds_read_u16_d16_hi v210, v1
	ds_read_u16_d16_hi v211, v1 offset:272
	ds_read_u16_d16_hi v212, v1 offset:544
	ds_read_u16_d16_hi v213, v1 offset:816
	ds_read_u16_d16_hi v214, v1 offset:2176
	ds_read_u16_d16_hi v215, v1 offset:2448
	ds_read_u16_d16_hi v216, v1 offset:2720
	ds_read_u16_d16_hi v217, v1 offset:2992
	s_waitcnt lgkmcnt(7)
	v_mul_f32_e32 v226, v102, v210
	v_cvt_pk_bf16_f32 v226, v226, v226
	ds_write_b16 v1, v226
	s_waitcnt lgkmcnt(7)
	v_mul_f32_e32 v227, v103, v211
	v_cvt_pk_bf16_f32 v227, v227, v227
	ds_write_b16 v1, v227 offset:272
	s_waitcnt lgkmcnt(7)
	v_mul_f32_e32 v228, v104, v212
	v_cvt_pk_bf16_f32 v228, v228, v228
	ds_write_b16 v1, v228 offset:544
	s_waitcnt lgkmcnt(7)
	v_mul_f32_e32 v229, v105, v213
	v_cvt_pk_bf16_f32 v229, v229, v229
	ds_write_b16 v1, v229 offset:816
	s_waitcnt lgkmcnt(7)
	v_mul_f32_e32 v226, v106, v214
	v_cvt_pk_bf16_f32 v226, v226, v226
	ds_write_b16 v1, v226 offset:2176
	s_waitcnt lgkmcnt(7)
	v_mul_f32_e32 v227, v107, v215
	v_cvt_pk_bf16_f32 v227, v227, v227
	ds_write_b16 v1, v227 offset:2448
	s_waitcnt lgkmcnt(7)
	v_mul_f32_e32 v228, v108, v216
	v_cvt_pk_bf16_f32 v228, v228, v228
	ds_write_b16 v1, v228 offset:2720
	s_waitcnt lgkmcnt(7)
	v_mul_f32_e32 v229, v109, v217
	v_cvt_pk_bf16_f32 v229, v229, v229
	ds_write_b16 v1, v229 offset:2992
	s_waitcnt lgkmcnt(7)
	ds_read_u16_d16_hi v218, v1 offset:4352
	ds_read_u16_d16_hi v219, v1 offset:4624
	ds_read_u16_d16_hi v220, v1 offset:4896
	ds_read_u16_d16_hi v221, v1 offset:5168
	ds_read_u16_d16_hi v222, v1 offset:6528
	ds_read_u16_d16_hi v223, v1 offset:6800
	ds_read_u16_d16_hi v224, v1 offset:7072
	ds_read_u16_d16_hi v225, v1 offset:7344
	s_waitcnt lgkmcnt(7)
	v_mul_f32_e32 v226, v110, v218
	v_cvt_pk_bf16_f32 v226, v226, v226
	ds_write_b16 v1, v226 offset:4352
	s_waitcnt lgkmcnt(7)
	v_mul_f32_e32 v227, v111, v219
	v_cvt_pk_bf16_f32 v227, v227, v227
	ds_write_b16 v1, v227 offset:4624
	s_waitcnt lgkmcnt(7)
	v_mul_f32_e32 v228, v112, v220
	v_cvt_pk_bf16_f32 v228, v228, v228
	ds_write_b16 v1, v228 offset:4896
	s_waitcnt lgkmcnt(7)
	v_mul_f32_e32 v229, v113, v221
	v_cvt_pk_bf16_f32 v229, v229, v229
	ds_write_b16 v1, v229 offset:5168
	s_waitcnt lgkmcnt(7)
	v_mul_f32_e32 v226, v114, v222
	v_cvt_pk_bf16_f32 v226, v226, v226
	ds_write_b16 v1, v226 offset:6528
	s_waitcnt lgkmcnt(7)
	v_mul_f32_e32 v227, v115, v223
	v_cvt_pk_bf16_f32 v227, v227, v227
	ds_write_b16 v1, v227 offset:6800
	s_waitcnt lgkmcnt(7)
	v_mul_f32_e32 v228, v116, v224
	v_cvt_pk_bf16_f32 v228, v228, v228
	ds_write_b16 v1, v228 offset:7072
	s_waitcnt lgkmcnt(7)
	v_mul_f32_e32 v229, v117, v225
	v_cvt_pk_bf16_f32 v229, v229, v229
	ds_write_b16 v1, v229 offset:7344
	s_waitcnt lgkmcnt(7)
	ds_read_u16_d16_hi v210, v1 offset:64
	ds_read_u16_d16_hi v211, v1 offset:336
	ds_read_u16_d16_hi v212, v1 offset:608
	ds_read_u16_d16_hi v213, v1 offset:880
	ds_read_u16_d16_hi v214, v1 offset:2240
	ds_read_u16_d16_hi v215, v1 offset:2512
	ds_read_u16_d16_hi v216, v1 offset:2784
	ds_read_u16_d16_hi v217, v1 offset:3056
	s_waitcnt lgkmcnt(7)
	v_mul_f32_e32 v226, v70, v210
	v_cvt_pk_bf16_f32 v226, v226, v226
	ds_write_b16 v1, v226 offset:64
	s_waitcnt lgkmcnt(7)
	v_mul_f32_e32 v227, v71, v211
	v_cvt_pk_bf16_f32 v227, v227, v227
	ds_write_b16 v1, v227 offset:336
	s_waitcnt lgkmcnt(7)
	v_mul_f32_e32 v228, v72, v212
	v_cvt_pk_bf16_f32 v228, v228, v228
	ds_write_b16 v1, v228 offset:608
	s_waitcnt lgkmcnt(7)
	v_mul_f32_e32 v229, v73, v213
	v_cvt_pk_bf16_f32 v229, v229, v229
	ds_write_b16 v1, v229 offset:880
	s_waitcnt lgkmcnt(7)
	v_mul_f32_e32 v226, v74, v214
	v_cvt_pk_bf16_f32 v226, v226, v226
	ds_write_b16 v1, v226 offset:2240
	s_waitcnt lgkmcnt(7)
	v_mul_f32_e32 v227, v75, v215
	v_cvt_pk_bf16_f32 v227, v227, v227
	ds_write_b16 v1, v227 offset:2512
	s_waitcnt lgkmcnt(7)
	v_mul_f32_e32 v228, v76, v216
	v_cvt_pk_bf16_f32 v228, v228, v228
	ds_write_b16 v1, v228 offset:2784
	s_waitcnt lgkmcnt(7)
	v_mul_f32_e32 v229, v77, v217
	v_cvt_pk_bf16_f32 v229, v229, v229
	ds_write_b16 v1, v229 offset:3056
	s_waitcnt lgkmcnt(7)
	ds_read_u16_d16_hi v218, v1 offset:4416
	ds_read_u16_d16_hi v219, v1 offset:4688
	ds_read_u16_d16_hi v220, v1 offset:4960
	ds_read_u16_d16_hi v221, v1 offset:5232
	ds_read_u16_d16_hi v222, v1 offset:6592
	ds_read_u16_d16_hi v223, v1 offset:6864
	ds_read_u16_d16_hi v224, v1 offset:7136
	ds_read_u16_d16_hi v225, v1 offset:7408
	s_waitcnt lgkmcnt(7)
	v_mul_f32_e32 v226, v78, v218
	v_cvt_pk_bf16_f32 v226, v226, v226
	ds_write_b16 v1, v226 offset:4416
	s_waitcnt lgkmcnt(7)
	v_mul_f32_e32 v227, v79, v219
	v_cvt_pk_bf16_f32 v227, v227, v227
	ds_write_b16 v1, v227 offset:4688
	s_waitcnt lgkmcnt(7)
	v_mul_f32_e32 v228, v80, v220
	v_cvt_pk_bf16_f32 v228, v228, v228
	ds_write_b16 v1, v228 offset:4960
	s_waitcnt lgkmcnt(7)
	v_mul_f32_e32 v229, v81, v221
	v_cvt_pk_bf16_f32 v229, v229, v229
	ds_write_b16 v1, v229 offset:5232
	s_waitcnt lgkmcnt(7)
	v_mul_f32_e32 v226, v82, v222
	v_cvt_pk_bf16_f32 v226, v226, v226
	ds_write_b16 v1, v226 offset:6592
	s_waitcnt lgkmcnt(7)
	v_mul_f32_e32 v227, v83, v223
	v_cvt_pk_bf16_f32 v227, v227, v227
	ds_write_b16 v1, v227 offset:6864
	s_waitcnt lgkmcnt(7)
	v_mul_f32_e32 v228, v84, v224
	v_cvt_pk_bf16_f32 v228, v228, v228
	ds_write_b16 v1, v228 offset:7136
	s_waitcnt lgkmcnt(7)
	v_mul_f32_e32 v229, v85, v225
	v_cvt_pk_bf16_f32 v229, v229, v229
	ds_write_b16 v1, v229 offset:7408
	s_waitcnt lgkmcnt(7)
	ds_read_u16_d16_hi v210, v1 offset:128
	ds_read_u16_d16_hi v211, v1 offset:400
	ds_read_u16_d16_hi v212, v1 offset:672
	ds_read_u16_d16_hi v213, v1 offset:944
	ds_read_u16_d16_hi v214, v1 offset:2304
	ds_read_u16_d16_hi v215, v1 offset:2576
	ds_read_u16_d16_hi v216, v1 offset:2848
	ds_read_u16_d16_hi v217, v1 offset:3120
	s_waitcnt lgkmcnt(7)
	v_mul_f32_e32 v226, v38, v210
	v_cvt_pk_bf16_f32 v226, v226, v226
	ds_write_b16 v1, v226 offset:128
	s_waitcnt lgkmcnt(7)
	v_mul_f32_e32 v227, v39, v211
	v_cvt_pk_bf16_f32 v227, v227, v227
	ds_write_b16 v1, v227 offset:400
	s_waitcnt lgkmcnt(7)
	v_mul_f32_e32 v228, v40, v212
	v_cvt_pk_bf16_f32 v228, v228, v228
	ds_write_b16 v1, v228 offset:672
	s_waitcnt lgkmcnt(7)
	v_mul_f32_e32 v229, v41, v213
	v_cvt_pk_bf16_f32 v229, v229, v229
	ds_write_b16 v1, v229 offset:944
	s_waitcnt lgkmcnt(7)
	v_mul_f32_e32 v226, v42, v214
	v_cvt_pk_bf16_f32 v226, v226, v226
	ds_write_b16 v1, v226 offset:2304
	s_waitcnt lgkmcnt(7)
	v_mul_f32_e32 v227, v43, v215
	v_cvt_pk_bf16_f32 v227, v227, v227
	ds_write_b16 v1, v227 offset:2576
	s_waitcnt lgkmcnt(7)
	v_mul_f32_e32 v228, v44, v216
	v_cvt_pk_bf16_f32 v228, v228, v228
	ds_write_b16 v1, v228 offset:2848
	s_waitcnt lgkmcnt(7)
	v_mul_f32_e32 v229, v45, v217
	v_cvt_pk_bf16_f32 v229, v229, v229
	ds_write_b16 v1, v229 offset:3120
	s_waitcnt lgkmcnt(7)
	ds_read_u16_d16_hi v218, v1 offset:4480
	ds_read_u16_d16_hi v219, v1 offset:4752
	ds_read_u16_d16_hi v220, v1 offset:5024
	ds_read_u16_d16_hi v221, v1 offset:5296
	ds_read_u16_d16_hi v222, v1 offset:6656
	ds_read_u16_d16_hi v223, v1 offset:6928
	ds_read_u16_d16_hi v224, v1 offset:7200
	ds_read_u16_d16_hi v225, v1 offset:7472
	s_waitcnt lgkmcnt(7)
	v_mul_f32_e32 v226, v46, v218
	v_cvt_pk_bf16_f32 v226, v226, v226
	ds_write_b16 v1, v226 offset:4480
	s_waitcnt lgkmcnt(7)
	v_mul_f32_e32 v227, v47, v219
	v_cvt_pk_bf16_f32 v227, v227, v227
	ds_write_b16 v1, v227 offset:4752
	s_waitcnt lgkmcnt(7)
	v_mul_f32_e32 v228, v48, v220
	v_cvt_pk_bf16_f32 v228, v228, v228
	ds_write_b16 v1, v228 offset:5024
	s_waitcnt lgkmcnt(7)
	v_mul_f32_e32 v229, v49, v221
	v_cvt_pk_bf16_f32 v229, v229, v229
	ds_write_b16 v1, v229 offset:5296
	s_waitcnt lgkmcnt(7)
	v_mul_f32_e32 v226, v50, v222
	v_cvt_pk_bf16_f32 v226, v226, v226
	ds_write_b16 v1, v226 offset:6656
	s_waitcnt lgkmcnt(7)
	v_mul_f32_e32 v227, v51, v223
	v_cvt_pk_bf16_f32 v227, v227, v227
	ds_write_b16 v1, v227 offset:6928
	s_waitcnt lgkmcnt(7)
	v_mul_f32_e32 v228, v52, v224
	v_cvt_pk_bf16_f32 v228, v228, v228
	ds_write_b16 v1, v228 offset:7200
	s_waitcnt lgkmcnt(7)
	v_mul_f32_e32 v229, v53, v225
	v_cvt_pk_bf16_f32 v229, v229, v229
	ds_write_b16 v1, v229 offset:7472
	s_waitcnt lgkmcnt(7)
	ds_read_u16_d16_hi v210, v1 offset:192
	ds_read_u16_d16_hi v211, v1 offset:464
	ds_read_u16_d16_hi v212, v1 offset:736
	ds_read_u16_d16_hi v213, v1 offset:1008
	ds_read_u16_d16_hi v214, v1 offset:2368
	ds_read_u16_d16_hi v215, v1 offset:2640
	ds_read_u16_d16_hi v216, v1 offset:2912
	ds_read_u16_d16_hi v217, v1 offset:3184
	s_waitcnt lgkmcnt(7)
	v_mul_f32_e32 v226, v6, v210
	v_cvt_pk_bf16_f32 v226, v226, v226
	ds_write_b16 v1, v226 offset:192
	s_waitcnt lgkmcnt(7)
	v_mul_f32_e32 v227, v7, v211
	v_cvt_pk_bf16_f32 v227, v227, v227
	ds_write_b16 v1, v227 offset:464
	s_waitcnt lgkmcnt(7)
	v_mul_f32_e32 v228, v8, v212
	v_cvt_pk_bf16_f32 v228, v228, v228
	ds_write_b16 v1, v228 offset:736
	s_waitcnt lgkmcnt(7)
	v_mul_f32_e32 v229, v9, v213
	v_cvt_pk_bf16_f32 v229, v229, v229
	ds_write_b16 v1, v229 offset:1008
	s_waitcnt lgkmcnt(7)
	v_mul_f32_e32 v226, v10, v214
	v_cvt_pk_bf16_f32 v226, v226, v226
	ds_write_b16 v1, v226 offset:2368
	s_waitcnt lgkmcnt(7)
	v_mul_f32_e32 v227, v11, v215
	v_cvt_pk_bf16_f32 v227, v227, v227
	ds_write_b16 v1, v227 offset:2640
	s_waitcnt lgkmcnt(7)
	v_mul_f32_e32 v228, v12, v216
	v_cvt_pk_bf16_f32 v228, v228, v228
	ds_write_b16 v1, v228 offset:2912
	s_waitcnt lgkmcnt(7)
	v_mul_f32_e32 v229, v13, v217
	v_cvt_pk_bf16_f32 v229, v229, v229
	ds_write_b16 v1, v229 offset:3184
	s_waitcnt lgkmcnt(7)
	ds_read_u16_d16_hi v218, v1 offset:4544
	ds_read_u16_d16_hi v219, v1 offset:4816
	ds_read_u16_d16_hi v220, v1 offset:5088
	ds_read_u16_d16_hi v221, v1 offset:5360
	ds_read_u16_d16_hi v222, v1 offset:6720
	ds_read_u16_d16_hi v223, v1 offset:6992
	ds_read_u16_d16_hi v224, v1 offset:7264
	ds_read_u16_d16_hi v225, v1 offset:7536
	s_waitcnt lgkmcnt(7)
	v_mul_f32_e32 v226, v14, v218
	v_cvt_pk_bf16_f32 v226, v226, v226
	ds_write_b16 v1, v226 offset:4544
	s_waitcnt lgkmcnt(7)
	v_mul_f32_e32 v227, v15, v219
	v_cvt_pk_bf16_f32 v227, v227, v227
	ds_write_b16 v1, v227 offset:4816
	s_waitcnt lgkmcnt(7)
	v_mul_f32_e32 v228, v16, v220
	v_cvt_pk_bf16_f32 v228, v228, v228
	ds_write_b16 v1, v228 offset:5088
	s_waitcnt lgkmcnt(7)
	v_mul_f32_e32 v229, v17, v221
	v_cvt_pk_bf16_f32 v229, v229, v229
	ds_write_b16 v1, v229 offset:5360
	s_waitcnt lgkmcnt(7)
	v_mul_f32_e32 v226, v18, v222
	v_cvt_pk_bf16_f32 v226, v226, v226
	ds_write_b16 v1, v226 offset:6720
	s_waitcnt lgkmcnt(7)
	v_mul_f32_e32 v227, v19, v223
	v_cvt_pk_bf16_f32 v227, v227, v227
	ds_write_b16 v1, v227 offset:6992
	s_waitcnt lgkmcnt(7)
	v_mul_f32_e32 v228, v20, v224
	v_cvt_pk_bf16_f32 v228, v228, v228
	ds_write_b16 v1, v228 offset:7264
	s_waitcnt lgkmcnt(7)
	v_mul_f32_e32 v229, v21, v225
	v_cvt_pk_bf16_f32 v229, v229, v229
	ds_write_b16 v1, v229 offset:7536
	s_waitcnt lgkmcnt(7)
	ds_read_b128 v[178:181], v0
	ds_read_b128 v[182:185], v0 offset:1088
	ds_read_b128 v[186:189], v0 offset:2176
	ds_read_b128 v[190:193], v0 offset:3264
	ds_read_b128 v[194:197], v0 offset:4352
	ds_read_b128 v[198:201], v0 offset:5440
	ds_read_b128 v[202:205], v0 offset:6528
	ds_read_b128 v[206:209], v0 offset:7616
	s_add_u32 s74, s72, 0x400000
	s_addc_u32 s75, s73, 0
	s_waitcnt lgkmcnt(7)
	global_store_dwordx4 v3, v[178:181], s[74:75]
	s_add_u32 s74, s72, 0x480000
	s_addc_u32 s75, s73, 0
	s_waitcnt lgkmcnt(6)
	global_store_dwordx4 v3, v[182:185], s[74:75]
	s_add_u32 s74, s72, 0x500000
	s_addc_u32 s75, s73, 0
	s_waitcnt lgkmcnt(5)
	global_store_dwordx4 v3, v[186:189], s[74:75]
	s_add_u32 s74, s72, 0x580000
	s_addc_u32 s75, s73, 0
	s_waitcnt lgkmcnt(4)
	global_store_dwordx4 v3, v[190:193], s[74:75]
	s_add_u32 s74, s72, 0x600000
	s_addc_u32 s75, s73, 0
	s_waitcnt lgkmcnt(3)
	global_store_dwordx4 v3, v[194:197], s[74:75]
	s_add_u32 s74, s72, 0x680000
	s_addc_u32 s75, s73, 0
	s_waitcnt lgkmcnt(2)
	global_store_dwordx4 v3, v[198:201], s[74:75]
	s_add_u32 s74, s72, 0x700000
	s_addc_u32 s75, s73, 0
	s_waitcnt lgkmcnt(1)
	global_store_dwordx4 v3, v[202:205], s[74:75]
	s_add_u32 s74, s72, 0x780000
	s_addc_u32 s75, s73, 0
	s_waitcnt lgkmcnt(0)
	global_store_dwordx4 v3, v[206:209], s[74:75]
